# attention: during a unit's last key-block iteration, touch the next attention unit's Q tile and first K/V block (L2 prefetch) so its prologue loads hit L2; on v65
# baseline (speedup 1.0000x reference)
; __device__ __forceinline__ void tile_ld(v4u (&raw)[4], const bf16* proj, int tok0, int colbase, int tid) {
;     const int c = tid & 15, r0 = tid >> 4;
; #pragma unroll
;     for (int p = 0; p < 4; ++p) raw[p] = *(const v4u*)(proj + (size_t)(tok0 + r0 + 32 * p) * INW + colbase + 8 * c);
; __device__ __forceinline__ void attn_unit(const bf16* proj, unsigned char* ws, LAS unsigned char* lds, int a) {
;     ...
;     for (int kb = kb0; kb <= kb1; ++kb) {
;         if (kb != kb0) __syncthreads();
;         tile_st<QK_STRIDE>(kr, KS, tid); tile_st<V_STRIDE>(vr, VS, tid);
;         __syncthreads();
;         if (kb < kb1) { tile_ld(kr, proj, tok0 + (kb + 1 - n) * 128, C_K + kvh * 128, tid); tile_ld(vr, proj, tok0 + (kb + 1 - n) * 128, C_V + kvh * 128, tid); }
.LBB0_606:
	s_cmp_ge_u32 s70, s71
	s_cselect_b64 s[54:55], -1, 0
	s_and_b64 vcc, exec, s[54:55]
	s_waitcnt vmcnt(7)
	ds_write_b128 v182, v[0:3]
	s_waitcnt vmcnt(5)
	ds_write_b128 v182, v[8:11] offset:8704
	s_waitcnt vmcnt(3)
	ds_write_b128 v182, v[16:19] offset:17408
	s_waitcnt vmcnt(1)
	ds_write_b128 v182, v[24:27] offset:26112
	ds_write_b128 v183, v[4:7]
	ds_write_b128 v183, v[12:15] offset:9216
	ds_write_b128 v183, v[20:23] offset:18432
	s_waitcnt vmcnt(0)
	ds_write_b128 v183, v[28:31] offset:27648
	s_waitcnt lgkmcnt(0)
	s_barrier
	s_cbranch_vccnz .Lapf
	v_add_u32_e32 v0, s51, v206
	v_add_u32_e32 v1, 0x80, v0
	v_mad_i64_i32 v[4:5], s[0:1], v1, s60, v[164:165]
	v_add_u32_e32 v1, 0xa0, v0
	v_mad_i64_i32 v[12:13], s[0:1], v1, s60, v[164:165]
	v_add_u32_e32 v1, 0xc0, v0
	v_add_u32_e32 v0, 0xe0, v0
	v_mad_i64_i32 v[20:21], s[0:1], v1, s60, v[164:165]
	v_mad_i64_i32 v[28:29], s[0:1], v0, s60, v[164:165]
	global_load_dwordx4 v[0:3], v[4:5], off offset:2048
	s_nop 0
	global_load_dwordx4 v[4:7], v[4:5], off offset:2560
	s_nop 0
	global_load_dwordx4 v[8:11], v[12:13], off offset:2048
	s_nop 0
	global_load_dwordx4 v[12:15], v[12:13], off offset:2560
	s_nop 0
	global_load_dwordx4 v[16:19], v[20:21], off offset:2048
	s_nop 0
	global_load_dwordx4 v[20:23], v[20:21], off offset:2560
	s_nop 0
	global_load_dwordx4 v[24:27], v[28:29], off offset:2048
	s_nop 0
	global_load_dwordx4 v[28:31], v[28:29], off offset:2560
	s_branch .LBB0_608
.Lapf:
	s_add_i32 s74, s68, s30
	s_cmpk_gt_i32 s74, 0x1ff
	s_cbranch_scc1 .LBB0_608
	s_ashr_i32 s75, s74, 2
	s_bfe_u32 s76, s74, 0x10001
	s_lshl_b32 s77, s74, 1
	s_and_b32 s77, s77, 2
	s_cmp_lt_i32 s75, 64
	s_cselect_b32 s78, 31, 15
	s_and_b32 s79, s78, s75
	s_lshl_b32 s82, s76, 2
	s_or_b32 s82, s82, s77
	s_lshl_b32 s82, s82, 8
	s_add_u32 s80, s26, s82
	s_addc_u32 s81, s27, 0
	v_ashrrev_i32_e32 v16, 4, v160
	v_lshlrev_b32_e32 v18, 4, v160
	v_and_b32_e32 v18, 0xf0, v18
	v_mov_b32_e32 v19, 0
	s_lshl_b32 s82, s75, 7
	v_lshl_add_u64 v[20:21], s[80:81], 0, v[18:19]
	v_add_u32_e32 v17, s82, v16
	v_add_u32_e32 v26, 0, v17
	v_mad_i64_i32 v[22:23], s[84:85], v26, s60, v[20:21]
	global_load_dword v0, v[22:23], off
	global_load_dword v1, v[22:23], off offset:256
	v_add_u32_e32 v26, 32, v17
	v_mad_i64_i32 v[22:23], s[84:85], v26, s60, v[20:21]
	global_load_dword v2, v[22:23], off
	global_load_dword v3, v[22:23], off offset:256
	v_add_u32_e32 v26, 64, v17
	v_mad_i64_i32 v[22:23], s[84:85], v26, s60, v[20:21]
	global_load_dword v4, v[22:23], off
	global_load_dword v5, v[22:23], off offset:256
	v_add_u32_e32 v26, 96, v17
	v_mad_i64_i32 v[22:23], s[84:85], v26, s60, v[20:21]
	global_load_dword v6, v[22:23], off
	global_load_dword v7, v[22:23], off offset:256
	s_sub_i32 s83, s79, 1
	s_max_i32 s83, s83, 0
	s_sub_i32 s82, s75, s79
	s_add_i32 s82, s82, s83
	s_lshl_b32 s82, s82, 7
	v_add_u32_e32 v17, s82, v16
	s_lshl_b32 s82, s76, 8
	s_add_u32 s80, s26, s82
	s_addc_u32 s81, s27, 0
	v_lshl_add_u64 v[20:21], s[80:81], 0, v[18:19]
	v_add_u32_e32 v26, 0, v17
	v_mad_i64_i32 v[22:23], s[84:85], v26, s60, v[20:21]
	global_load_dword v8, v[22:23], off offset:2048
	global_load_dword v9, v[22:23], off offset:2560
	v_add_u32_e32 v26, 32, v17
	v_mad_i64_i32 v[22:23], s[84:85], v26, s60, v[20:21]
	global_load_dword v10, v[22:23], off offset:2048
	global_load_dword v11, v[22:23], off offset:2560
	v_add_u32_e32 v26, 64, v17
	v_mad_i64_i32 v[22:23], s[84:85], v26, s60, v[20:21]
	global_load_dword v12, v[22:23], off offset:2048
	global_load_dword v13, v[22:23], off offset:2560
	v_add_u32_e32 v26, 96, v17
	v_mad_i64_i32 v[22:23], s[84:85], v26, s60, v[20:21]
	global_load_dword v14, v[22:23], off offset:2048
	global_load_dword v15, v[22:23], off offset:2560

; __device__ __forceinline__ void attn_unit(const bf16* proj, unsigned char* ws, LAS unsigned char* lds, int a) {
;     ...
; #pragma unroll
;     for (int rt = 0; rt < 2; ++rt) {
;         float lt = lrow[rt]; lt += __shfl_xor(lt, 16); lt += __shfl_xor(lt, 32);
;         const float inv = 1.0f / lt; const int tok = tok0 + rq * 32 + rt * 16 + fr; float ss = 0.f;
;         bf16* orow = mix + (size_t)tok * D + h * 128 + 4 * fq;
.LBB0_614:
	s_waitcnt vmcnt(0)
	s_mov_b64 s[4:5], 0
